# v048 barrier items re-sequenced: layer-0 gate/up first (15360), g3 converters in layers 0-2
# speedup vs baseline: 1.0141x; 1.0012x over previous
; DEV void phase_prologue_a(const Frame& F0) {
;     ...
;         constexpr int GU_NB = 2 * FF / 32, GU_ITEMS = 16 * GU_NB;
;         for (int it = F.gw; it < NE * GU_ITEMS; it += F.NGW) { const int e = it / GU_ITEMS, r = it % GU_ITEMS, kb = r / GU_NB, nb = r % GU_NB; const int d0 = 32 * nb, j = d0 >> 8, w = d0 & 255;
;             const float* src = (w < 128 ? GIN(I_WGATE) : GIN(I_WUP)) + ((size_t)l * NE + e) * 1024 * FF;
;             tr_item(src, FF, 128 * j + (w & 127), 64 * kb, (bf16_t*)(F.ws + WS_WGU) + ((size_t)l * NE + e) * 2 * FF * 1024, 1024, d0, scr, F.lane); }
.LBB0_24:
	s_andn2_b64 vcc, exec, s[10:11]
	s_cbranch_vccnz .LBB0_29
	s_lshl_b64 s[20:21], s[2:3], 27
	s_mov_b32 s28, s31
	v_readlane_b32 s100, v255, 51
	s_cmp_lg_u32 s100, 0x100
	s_cbranch_scc1 .Lpro_gu_all
	s_cmp_lg_u32 s14, 0
	s_cbranch_scc1 .LBB0_29
	s_add_i32 s28, s28, 0x6c00

; #define WAIT_VM(n) do {} while (0)
; #define WAIT_ALL() do {} while (0)
; #define LAUNDER_S(x) do {} while (0)
; #define WAIT_VM(n) asm volatile("s_waitcnt vmcnt(" #n ")" ::: "memory")
; #define WAIT_ALL() asm volatile("s_waitcnt vmcnt(0) lgkmcnt(0)" ::: "memory")
; #define LAUNDER_S(x) asm volatile("" : "+s"(x))
; DEV int lane_id() { return (int)__builtin_amdgcn_mbcnt_hi(~0u, __builtin_amdgcn_mbcnt_lo(~0u, 0u)); }
; DEV unsigned xb_ld(unsigned* p) { return __hip_atomic_load(p, __ATOMIC_RELAXED, __HIP_MEMORY_SCOPE_AGENT); }
; DEV unsigned xb_add(unsigned* p, unsigned v) { return __hip_atomic_fetch_add(p, v, __ATOMIC_RELAXED, __HIP_MEMORY_SCOPE_AGENT); }
; DEV void fence_acquire() { __builtin_amdgcn_fence(__ATOMIC_ACQUIRE, "agent"); }
; DEV void fence_release() { __builtin_amdgcn_fence(__ATOMIC_RELEASE, "agent"); }
; #define XB_SPIN(cond, bar) do { unsigned _sp = 0; while (cond) { s_sleep1(); \
;     if ((++_sp & 255u) == 0u) { if (xb_ld(&(bar)[XB_TMO])) break; if (_sp > XB_SPIN_CAP) { xb_add(&(bar)[XB_TMO], 1u); break; } } } } while (0)
; DEV void xcd_barrier(const XcdBarrier& b) {
;     WAIT_VM(0);
;     __syncthreads();
;     int bw = b.wave; LAUNDER_S(bw);
;     if (bw == 0 && lane_id() == 0) {
;         unsigned* bar = b.bar; LAUNDER_S(bar);
;         unsigned bx = b.x; LAUNDER_S(bx);
;         WAIT_ALL();
;         unsigned nloc = b.st[0], nx = b.st[1];
;         if (nloc == 0u) { xcd_barrier_complete(bar, bx, nloc, nx); b.st[0] = nloc; b.st[1] = nx; }
;         const unsigned old = xb_add(&bar[XB_XSUB(bx)], 1u);
;         const unsigned gen = old / nloc;
;         if (old + 1u == (gen + 1u) * nloc) {
;             fence_release();
;             WAIT_VM(0);
;             const unsigned og = xb_add(&bar[XB_TOP], 1u);
;             const unsigned tg = og / nx;
;             if (og + 1u == (tg + 1u) * nx) xb_add(&bar[XB_TOPGEN], 1u);
;             else XB_SPIN(xb_ld(&bar[XB_TOPGEN]) == tg, bar);
;             fence_acquire();
;             xb_add(&bar[XB_XGEN(bx)], 1u);
;             WAIT_VM(0);
;         } else {
;             XB_SPIN(xb_ld(&bar[XB_XGEN(bx)]) == gen, bar);
;             fence_acquire();
;             WAIT_VM(0);
;         }
;     }
;     __syncthreads();
; }
.LBB0_115:
	s_or_b64 exec, exec, s[30:31]
	s_cselect_b32 s38, 1, 0
	v_writelane_b32 v255, s38, 61
	v_readlane_b32 s38, v255, 59
	s_add_i32 s39, s38, 1
	v_writelane_b32 v255, s39, 59
	s_mov_b32 s41, 0
	v_readlane_b32 s39, v251, 29
	s_cmp_eq_u32 s39, 0
	s_cbranch_scc1 .Lbw0_none
	v_readlane_b32 s40, v255, 51
	s_cmp_lg_u32 s40, 0x100
	s_cbranch_scc1 .Lbw0_none
	v_readlane_b32 s40, v255, 48
	s_mul_i32 s40, s40, 7
	s_mul_i32 s38, s38, 0x700
	s_add_i32 s40, s40, s38
	s_add_i32 s40, s40, s39
	s_add_i32 s40, s40, -1
	s_cmp_lt_u32 s40, 0x11f00
	s_cbranch_scc0 .Lbw0_none
	s_mov_b32 s41, 0
	s_add_i32 s40, s40, 0x3000
	s_cmp_lt_u32 s40, 0x6c00
	s_cbranch_scc1 .Lbw0_have
	s_mov_b32 s41, 1
	s_sub_i32 s40, s40, 0x6c00
	s_cmp_lt_u32 s40, 0x5000
	s_cbranch_scc1 .Lbw0_have
	s_mov_b32 s41, 2
	s_sub_i32 s40, s40, 0x5000
	s_cmp_lt_u32 s40, 0x4600
	s_cbranch_scc1 .Lbw0_have
	s_mov_b32 s41, 3
	s_sub_i32 s40, s40, 0x4600

; #define WAIT_VM(n) do {} while (0)
; #define WAIT_ALL() do {} while (0)
; #define LAUNDER_S(x) do {} while (0)
; #define WAIT_VM(n) asm volatile("s_waitcnt vmcnt(" #n ")" ::: "memory")
; #define WAIT_ALL() asm volatile("s_waitcnt vmcnt(0) lgkmcnt(0)" ::: "memory")
; #define LAUNDER_S(x) asm volatile("" : "+s"(x))
; DEV int lane_id() { return (int)__builtin_amdgcn_mbcnt_hi(~0u, __builtin_amdgcn_mbcnt_lo(~0u, 0u)); }
; DEV unsigned xb_ld(unsigned* p) { return __hip_atomic_load(p, __ATOMIC_RELAXED, __HIP_MEMORY_SCOPE_AGENT); }
; DEV unsigned xb_add(unsigned* p, unsigned v) { return __hip_atomic_fetch_add(p, v, __ATOMIC_RELAXED, __HIP_MEMORY_SCOPE_AGENT); }
; DEV void fence_acquire() { __builtin_amdgcn_fence(__ATOMIC_ACQUIRE, "agent"); }
; DEV void fence_release() { __builtin_amdgcn_fence(__ATOMIC_RELEASE, "agent"); }
; #define XB_SPIN(cond, bar) do { unsigned _sp = 0; while (cond) { s_sleep1(); \
;     if ((++_sp & 255u) == 0u) { if (xb_ld(&(bar)[XB_TMO])) break; if (_sp > XB_SPIN_CAP) { xb_add(&(bar)[XB_TMO], 1u); break; } } } } while (0)
; DEV void xcd_barrier(const XcdBarrier& b) {
;     WAIT_VM(0);
;     __syncthreads();
;     int bw = b.wave; LAUNDER_S(bw);
;     if (bw == 0 && lane_id() == 0) {
;         unsigned* bar = b.bar; LAUNDER_S(bar);
;         unsigned bx = b.x; LAUNDER_S(bx);
;         WAIT_ALL();
;         unsigned nloc = b.st[0], nx = b.st[1];
;         if (nloc == 0u) { xcd_barrier_complete(bar, bx, nloc, nx); b.st[0] = nloc; b.st[1] = nx; }
;         const unsigned old = xb_add(&bar[XB_XSUB(bx)], 1u);
;         const unsigned gen = old / nloc;
;         if (old + 1u == (gen + 1u) * nloc) {
;             fence_release();
;             WAIT_VM(0);
;             const unsigned og = xb_add(&bar[XB_TOP], 1u);
;             const unsigned tg = og / nx;
;             if (og + 1u == (tg + 1u) * nx) xb_add(&bar[XB_TOPGEN], 1u);
;             else XB_SPIN(xb_ld(&bar[XB_TOPGEN]) == tg, bar);
;             fence_acquire();
;             xb_add(&bar[XB_XGEN(bx)], 1u);
;             WAIT_VM(0);
;         } else {
;             XB_SPIN(xb_ld(&bar[XB_XGEN(bx)]) == gen, bar);
;             fence_acquire();
;             WAIT_VM(0);
;         }
;     }
;     __syncthreads();
; }
.LBB0_241:
	v_writelane_b32 v253, s58, 51
	s_nop 1
	v_writelane_b32 v253, s59, 52
	v_writelane_b32 v253, s56, 53
	s_nop 1
	v_writelane_b32 v253, s57, 54
	s_or_b64 exec, exec, s[34:35]
	s_cselect_b32 s38, 1, 0
	v_writelane_b32 v255, s38, 61
	v_readlane_b32 s38, v255, 59
	s_add_i32 s39, s38, 1
	v_writelane_b32 v255, s39, 59
	s_mov_b32 s41, 0
	v_readlane_b32 s39, v251, 29
	s_cmp_eq_u32 s39, 0
	s_cbranch_scc1 .Lbw2_none
	v_readlane_b32 s40, v255, 51
	s_cmp_lg_u32 s40, 0x100
	s_cbranch_scc1 .Lbw2_none
	v_readlane_b32 s40, v255, 48
	s_mul_i32 s40, s40, 7
	s_mul_i32 s38, s38, 0x700
	s_add_i32 s40, s40, s38
	s_add_i32 s40, s40, s39
	s_add_i32 s40, s40, -1
	s_cmp_lt_u32 s40, 0x11f00
	s_cbranch_scc0 .Lbw2_none
	s_mov_b32 s41, 0
	s_add_i32 s40, s40, 0x3000
	s_cmp_lt_u32 s40, 0x6c00
	s_cbranch_scc1 .Lbw2_have
	s_mov_b32 s41, 1
	s_sub_i32 s40, s40, 0x6c00
	s_cmp_lt_u32 s40, 0x5000
	s_cbranch_scc1 .Lbw2_have
	s_mov_b32 s41, 2
	s_sub_i32 s40, s40, 0x5000
	s_cmp_lt_u32 s40, 0x4600
	s_cbranch_scc1 .Lbw2_have
	s_mov_b32 s41, 3
	s_sub_i32 s40, s40, 0x4600

; #define WAIT_VM(n) do {} while (0)
; #define WAIT_ALL() do {} while (0)
; #define LAUNDER_S(x) do {} while (0)
; #define WAIT_VM(n) asm volatile("s_waitcnt vmcnt(" #n ")" ::: "memory")
; #define WAIT_ALL() asm volatile("s_waitcnt vmcnt(0) lgkmcnt(0)" ::: "memory")
; #define LAUNDER_S(x) asm volatile("" : "+s"(x))
; DEV int lane_id() { return (int)__builtin_amdgcn_mbcnt_hi(~0u, __builtin_amdgcn_mbcnt_lo(~0u, 0u)); }
; DEV unsigned xb_ld(unsigned* p) { return __hip_atomic_load(p, __ATOMIC_RELAXED, __HIP_MEMORY_SCOPE_AGENT); }
; DEV unsigned xb_add(unsigned* p, unsigned v) { return __hip_atomic_fetch_add(p, v, __ATOMIC_RELAXED, __HIP_MEMORY_SCOPE_AGENT); }
; DEV void fence_acquire() { __builtin_amdgcn_fence(__ATOMIC_ACQUIRE, "agent"); }
; DEV void fence_release() { __builtin_amdgcn_fence(__ATOMIC_RELEASE, "agent"); }
; #define XB_SPIN(cond, bar) do { unsigned _sp = 0; while (cond) { s_sleep1(); \
;     if ((++_sp & 255u) == 0u) { if (xb_ld(&(bar)[XB_TMO])) break; if (_sp > XB_SPIN_CAP) { xb_add(&(bar)[XB_TMO], 1u); break; } } } } while (0)
; DEV void xcd_barrier(const XcdBarrier& b) {
;     WAIT_VM(0);
;     __syncthreads();
;     int bw = b.wave; LAUNDER_S(bw);
;     if (bw == 0 && lane_id() == 0) {
;         unsigned* bar = b.bar; LAUNDER_S(bar);
;         unsigned bx = b.x; LAUNDER_S(bx);
;         WAIT_ALL();
;         unsigned nloc = b.st[0], nx = b.st[1];
;         if (nloc == 0u) { xcd_barrier_complete(bar, bx, nloc, nx); b.st[0] = nloc; b.st[1] = nx; }
;         const unsigned old = xb_add(&bar[XB_XSUB(bx)], 1u);
;         const unsigned gen = old / nloc;
;         if (old + 1u == (gen + 1u) * nloc) {
;             fence_release();
;             WAIT_VM(0);
;             const unsigned og = xb_add(&bar[XB_TOP], 1u);
;             const unsigned tg = og / nx;
;             if (og + 1u == (tg + 1u) * nx) xb_add(&bar[XB_TOPGEN], 1u);
;             else XB_SPIN(xb_ld(&bar[XB_TOPGEN]) == tg, bar);
;             fence_acquire();
;             xb_add(&bar[XB_XGEN(bx)], 1u);
;             WAIT_VM(0);
;         } else {
;             XB_SPIN(xb_ld(&bar[XB_XGEN(bx)]) == gen, bar);
;             fence_acquire();
;             WAIT_VM(0);
;         }
;     }
;     __syncthreads();
; }
.LBB0_422:
	s_or_b64 exec, exec, s[34:35]
	s_cselect_b32 s38, 1, 0
	v_writelane_b32 v255, s38, 61
	v_readlane_b32 s38, v255, 59
	s_add_i32 s39, s38, 1
	v_writelane_b32 v255, s39, 59
	s_mov_b32 s41, 0
	v_readlane_b32 s39, v251, 29
	s_cmp_eq_u32 s39, 0
	s_cbranch_scc1 .Lbw3_none
	v_readlane_b32 s40, v255, 51
	s_cmp_lg_u32 s40, 0x100
	s_cbranch_scc1 .Lbw3_none
	v_readlane_b32 s40, v255, 48
	s_mul_i32 s40, s40, 7
	s_mul_i32 s38, s38, 0x700
	s_add_i32 s40, s40, s38
	s_add_i32 s40, s40, s39
	s_add_i32 s40, s40, -1
	s_cmp_lt_u32 s40, 0x11f00
	s_cbranch_scc0 .Lbw3_none
	s_mov_b32 s41, 0
	s_add_i32 s40, s40, 0x3000
	s_cmp_lt_u32 s40, 0x6c00
	s_cbranch_scc1 .Lbw3_have
	s_mov_b32 s41, 1
	s_sub_i32 s40, s40, 0x6c00
	s_cmp_lt_u32 s40, 0x5000
	s_cbranch_scc1 .Lbw3_have
	s_mov_b32 s41, 2
	s_sub_i32 s40, s40, 0x5000
	s_cmp_lt_u32 s40, 0x4600
	s_cbranch_scc1 .Lbw3_have
	s_mov_b32 s41, 3
	s_sub_i32 s40, s40, 0x4600

; #define WAIT_VM(n) do {} while (0)
; #define WAIT_ALL() do {} while (0)
; #define LAUNDER_S(x) do {} while (0)
; #define WAIT_VM(n) asm volatile("s_waitcnt vmcnt(" #n ")" ::: "memory")
; #define WAIT_ALL() asm volatile("s_waitcnt vmcnt(0) lgkmcnt(0)" ::: "memory")
; #define LAUNDER_S(x) asm volatile("" : "+s"(x))
; DEV int lane_id() { return (int)__builtin_amdgcn_mbcnt_hi(~0u, __builtin_amdgcn_mbcnt_lo(~0u, 0u)); }
; DEV unsigned xb_ld(unsigned* p) { return __hip_atomic_load(p, __ATOMIC_RELAXED, __HIP_MEMORY_SCOPE_AGENT); }
; DEV unsigned xb_add(unsigned* p, unsigned v) { return __hip_atomic_fetch_add(p, v, __ATOMIC_RELAXED, __HIP_MEMORY_SCOPE_AGENT); }
; DEV void fence_acquire() { __builtin_amdgcn_fence(__ATOMIC_ACQUIRE, "agent"); }
; DEV void fence_release() { __builtin_amdgcn_fence(__ATOMIC_RELEASE, "agent"); }
; #define XB_SPIN(cond, bar) do { unsigned _sp = 0; while (cond) { s_sleep1(); \
;     if ((++_sp & 255u) == 0u) { if (xb_ld(&(bar)[XB_TMO])) break; if (_sp > XB_SPIN_CAP) { xb_add(&(bar)[XB_TMO], 1u); break; } } } } while (0)
; DEV void xcd_barrier(const XcdBarrier& b) {
;     WAIT_VM(0);
;     __syncthreads();
;     int bw = b.wave; LAUNDER_S(bw);
;     if (bw == 0 && lane_id() == 0) {
;         unsigned* bar = b.bar; LAUNDER_S(bar);
;         unsigned bx = b.x; LAUNDER_S(bx);
;         WAIT_ALL();
;         unsigned nloc = b.st[0], nx = b.st[1];
;         if (nloc == 0u) { xcd_barrier_complete(bar, bx, nloc, nx); b.st[0] = nloc; b.st[1] = nx; }
;         const unsigned old = xb_add(&bar[XB_XSUB(bx)], 1u);
;         const unsigned gen = old / nloc;
;         if (old + 1u == (gen + 1u) * nloc) {
;             fence_release();
;             WAIT_VM(0);
;             const unsigned og = xb_add(&bar[XB_TOP], 1u);
;             const unsigned tg = og / nx;
;             if (og + 1u == (tg + 1u) * nx) xb_add(&bar[XB_TOPGEN], 1u);
;             else XB_SPIN(xb_ld(&bar[XB_TOPGEN]) == tg, bar);
;             fence_acquire();
;             xb_add(&bar[XB_XGEN(bx)], 1u);
;             WAIT_VM(0);
;         } else {
;             XB_SPIN(xb_ld(&bar[XB_XGEN(bx)]) == gen, bar);
;             fence_acquire();
;             WAIT_VM(0);
;         }
;     }
;     __syncthreads();
; }
.Lxb4_join:
.LBB0_811:
	s_or_b64 exec, exec, s[34:35]
	s_cselect_b32 s38, 1, 0
	v_writelane_b32 v255, s38, 61
	v_readlane_b32 s38, v255, 59
	s_add_i32 s39, s38, 1
	v_writelane_b32 v255, s39, 59
	s_mov_b32 s41, 0
	v_readlane_b32 s39, v251, 29
	s_cmp_eq_u32 s39, 0
	s_cbranch_scc1 .Lbw4_none
	v_readlane_b32 s40, v255, 51
	s_cmp_lg_u32 s40, 0x100
	s_cbranch_scc1 .Lbw4_none
	v_readlane_b32 s40, v255, 48
	s_mul_i32 s40, s40, 7
	s_mul_i32 s38, s38, 0x700
	s_add_i32 s40, s40, s38
	s_add_i32 s40, s40, s39
	s_add_i32 s40, s40, -1
	s_cmp_lt_u32 s40, 0x11f00
	s_cbranch_scc0 .Lbw4_none
	s_mov_b32 s41, 0
	s_add_i32 s40, s40, 0x3000
	s_cmp_lt_u32 s40, 0x6c00
	s_cbranch_scc1 .Lbw4_have
	s_mov_b32 s41, 1
	s_sub_i32 s40, s40, 0x6c00
	s_cmp_lt_u32 s40, 0x5000
	s_cbranch_scc1 .Lbw4_have
	s_mov_b32 s41, 2
	s_sub_i32 s40, s40, 0x5000
	s_cmp_lt_u32 s40, 0x4600
	s_cbranch_scc1 .Lbw4_have
	s_mov_b32 s41, 3
	s_sub_i32 s40, s40, 0x4600

; DEV void gemm_g3(const Frame& F0, int l, int vcu) {
;     const Frame F = refresh(F0);
;     pg8::PlainOrder S; S.init((const void*)(F.ws + WS_MERGED), (const bf16_t*)(F.ws + WS_WOUT) + (size_t)l * 1024 * 1024, 1024, (l == DEPTH - 1) ? LATPAD : MPAD, 1024, F.G, vcu);
;     EpiP E; E.O = (bf16_t*)(F.ws + WS_Y); E.ldc = 1024;
;     pg8::gemm_phase(F.lds, 1024, S, E, F.wave, F.lane);
; }
.LBB0_1317:
	v_readlane_b32 s4, v251, 0
	v_readlane_b32 s6, v251, 2
	v_readlane_b32 s7, v251, 3
	s_lshl_b32 s0, s33, 2
	v_readlane_b32 s10, v251, 29
	v_mov_b32_e32 v16, v200
	s_mov_b64 s[2:3], s[6:7]
	s_cmp_ge_i32 s95, s0
	v_readlane_b32 s5, v251, 1
	s_cbranch_scc1 .LBB0_1333
	s_mov_b32 s100, s96
	v_readlane_b32 s101, v253, 62
	s_cmp_gt_u32 s101, 2
	s_cbranch_scc1 .Lg3d_norm
	v_readlane_b32 s101, v255, 51
	s_cmp_lg_u32 s101, 0x100
	s_cbranch_scc1 .Lg3d_norm
	s_movk_i32 s100, 0xa0
	v_readlane_b32 s101, v255, 48
	s_cmp_ge_u32 s101, 0xa0
	s_cbranch_scc1 .Lsg_entry

; #define LAS __attribute__((address_space(3)))
; #define NT_LOAD(p) __builtin_nontemporal_load(p)
; DEV void tr_item(const float* W, int ldw, int col0, int k0, bf16_t* WT, int K, int row0, LAS float* scr, int lane) {
; #pragma unroll 8
;     for (int i = 0; i < 32; ++i) { const int kk = 2 * i + (lane >> 5); scr[kk * 33 + (lane & 31)] = NT_LOAD(&W[(size_t)(k0 + kk) * ldw + col0 + (lane & 31)]); }
; DEV void phase_prologue_a(const Frame& F0) {
;     ...
;         constexpr int GU_NB = 2 * FF / 32, GU_ITEMS = 16 * GU_NB;
;         for (int it = F.gw; it < NE * GU_ITEMS; it += F.NGW) { const int e = it / GU_ITEMS, r = it % GU_ITEMS, kb = r / GU_NB, nb = r % GU_NB; const int d0 = 32 * nb, j = d0 >> 8, w = d0 & 255;
;             const float* src = (w < 128 ? GIN(I_WGATE) : GIN(I_WUP)) + ((size_t)l * NE + e) * 1024 * FF;
;             tr_item(src, FF, 128 * j + (w & 127), 64 * kb, (bf16_t*)(F.ws + WS_WGU) + ((size_t)l * NE + e) * 2 * FF * 1024, 1024, d0, scr, F.lane); }
.Lsg_entry:
	v_readlane_b32 s36, v253, 62
	s_cmp_gt_u32 s36, 2
	s_cbranch_scc1 .Lsg_done
	v_readlane_b32 s2, v255, 51
	s_cmp_lg_u32 s2, 0x100
	s_cbranch_scc1 .Lsg_done
	v_readlane_b32 s2, v255, 48
	s_cmp_lt_u32 s2, 0xa0
	s_cbranch_scc1 .Lsg_done
	v_readlane_b32 s3, v251, 29
	s_sub_i32 s2, s2, 0xa0
	s_lshl_b32 s2, s2, 3
	s_add_i32 s2, s2, s3
	v_readlane_b32 s6, v255, 53
	v_readlane_b32 s7, v255, 54
	v_readlane_b32 s4, v255, 55
	v_readlane_b32 s5, v255, 56
	v_readlane_b32 s34, v255, 57
	v_readlane_b32 s35, v255, 58
	s_add_u32 s6, s6, 0x2bc8000
	s_addc_u32 s7, s7, 0
	s_mov_b32 s8, 0
	s_mov_b32 s37, 0
	s_cmp_eq_u32 s36, 0
	s_cbranch_scc1 .Lsg_go
	s_mov_b32 s8, 0x8000000
	s_mov_b32 s37, 0x5000
	s_cmp_eq_u32 s36, 1
	s_cbranch_scc1 .Lsg_go
	s_mov_b32 s8, 0x10000000
	s_mov_b32 s37, 0x4600
.Lsg_go:
	s_add_u32 s4, s4, s8
	s_addc_u32 s5, s5, 0
	s_add_u32 s34, s34, s8
	s_addc_u32 s35, s35, 0
	s_add_u32 s6, s6, s8
	s_addc_u32 s7, s7, 0
	s_add_i32 s2, s2, s37
	s_add_i32 s101, s37, 0x3000
	s_lshl_b32 s30, s3, 14
	v_and_b32_e32 v120, 31, v200
	v_lshlrev_b32_e32 v2, 2, v120
	v_lshrrev_b32_e32 v3, 5, v200
	v_and_b32_e32 v4, 7, v200
	v_lshrrev_b32_e32 v6, 3, v200
	v_mul_u32_u24_e32 v7, 33, v3
	v_add_u32_e32 v7, v7, v120
	v_lshl_add_u32 v7, v7, 2, s30
	v_add_u32_e32 v8, 0x400, v7
	v_add_u32_e32 v9, 0x840, v7
	v_add_u32_e32 v10, 0xc40, v7
	v_add_u32_e32 v11, 0x1080, v7
	v_add_u32_e32 v12, 0x1480, v7
	v_add_u32_e32 v13, 0x18c0, v7
	v_add_u32_e32 v14, 0x1cc0, v7
	v_mul_u32_u24_e32 v120, 0x108, v4
	v_add_u32_e32 v120, v120, v6
	v_lshl_add_u32 v15, v120, 2, s30
	v_lshl_add_u32 v122, v3, 13, v2
	v_mov_b32_e32 v123, 0
	v_lshlrev_b32_e32 v124, 4, v4
	v_lshl_add_u32 v124, v6, 11, v124
	v_mov_b32_e32 v125, 0
	s_mov_b64 s[40:41], 0x20000
	s_mov_b64 s[42:43], 0x4000
	s_mov_b64 s[44:45], 0x4000
.Lsg_loop:
	s_lshr_b32 s8, s2, 11
	s_and_b32 s9, s2, 0x7ff
	s_lshr_b32 s10, s9, 7
	s_and_b32 s9, s9, 0x7f
	s_lshl_b32 s24, s10, 19
	s_lshr_b32 s25, s9, 3
	s_lshl_b32 s25, s25, 9
	s_add_i32 s24, s24, s25
	s_and_b32 s25, s9, 3
	s_lshl_b32 s25, s25, 7
	s_add_i32 s24, s24, s25
	s_lshr_b32 s29, s8, 9
	s_lshl_b32 s28, s8, 23
	s_add_u32 s28, s28, s24
	s_addc_u32 s29, s29, 0
	s_bitcmp0_b32 s9, 2
	s_cselect_b32 s24, s4, s34
	s_cselect_b32 s25, s5, s35
	s_add_u32 s28, s28, s24
	s_addc_u32 s29, s29, s25
	s_lshl_b32 s24, s9, 16
	s_lshl_b32 s25, s10, 7
	s_add_i32 s24, s24, s25
	s_lshr_b32 s11, s8, 9
	s_lshl_b32 s10, s8, 23
	s_add_u32 s10, s10, s24
	s_addc_u32 s11, s11, 0
	s_add_u32 s10, s10, s6
	s_addc_u32 s11, s11, s7
	v_lshl_add_u64 v[16:17], s[28:29], 0, v[122:123]
	v_lshl_add_u64 v[18:19], v[16:17], 0, s[44:45]
	v_lshl_add_u64 v[20:21], v[18:19], 0, s[44:45]
	v_lshl_add_u64 v[22:23], v[20:21], 0, s[44:45]
	v_lshl_add_u64 v[24:25], v[22:23], 0, s[44:45]
	v_lshl_add_u64 v[26:27], v[24:25], 0, s[44:45]
	v_lshl_add_u64 v[28:29], v[26:27], 0, s[44:45]
	v_lshl_add_u64 v[30:31], v[28:29], 0, s[44:45]
	global_load_dword v32, v[16:17], off nt
	global_load_dword v33, v[18:19], off nt
	global_load_dword v34, v[20:21], off nt
	global_load_dword v35, v[22:23], off nt
	global_load_dword v36, v[24:25], off nt
	global_load_dword v37, v[26:27], off nt
	global_load_dword v38, v[28:29], off nt
	global_load_dword v39, v[30:31], off nt
	v_lshl_add_u64 v[16:17], v[16:17], 0, s[40:41]
	v_lshl_add_u64 v[18:19], v[18:19], 0, s[40:41]
	v_lshl_add_u64 v[20:21], v[20:21], 0, s[40:41]
	v_lshl_add_u64 v[22:23], v[22:23], 0, s[40:41]
	v_lshl_add_u64 v[24:25], v[24:25], 0, s[40:41]
	v_lshl_add_u64 v[26:27], v[26:27], 0, s[40:41]
	v_lshl_add_u64 v[28:29], v[28:29], 0, s[40:41]
	v_lshl_add_u64 v[30:31], v[30:31], 0, s[40:41]
	global_load_dword v40, v[16:17], off nt
	global_load_dword v41, v[18:19], off nt
	global_load_dword v42, v[20:21], off nt
	global_load_dword v43, v[22:23], off nt
	global_load_dword v44, v[24:25], off nt
	global_load_dword v45, v[26:27], off nt
	global_load_dword v46, v[28:29], off nt
	global_load_dword v47, v[30:31], off nt
	v_lshl_add_u64 v[16:17], v[16:17], 0, s[40:41]
	v_lshl_add_u64 v[18:19], v[18:19], 0, s[40:41]
	v_lshl_add_u64 v[20:21], v[20:21], 0, s[40:41]
	v_lshl_add_u64 v[22:23], v[22:23], 0, s[40:41]
	v_lshl_add_u64 v[24:25], v[24:25], 0, s[40:41]
	v_lshl_add_u64 v[26:27], v[26:27], 0, s[40:41]
	v_lshl_add_u64 v[28:29], v[28:29], 0, s[40:41]
	v_lshl_add_u64 v[30:31], v[30:31], 0, s[40:41]
	global_load_dword v48, v[16:17], off nt
	global_load_dword v49, v[18:19], off nt
	global_load_dword v50, v[20:21], off nt
	global_load_dword v51, v[22:23], off nt
	global_load_dword v52, v[24:25], off nt
	global_load_dword v53, v[26:27], off nt
	global_load_dword v54, v[28:29], off nt
	global_load_dword v55, v[30:31], off nt
	v_lshl_add_u64 v[16:17], v[16:17], 0, s[40:41]
	v_lshl_add_u64 v[18:19], v[18:19], 0, s[40:41]
	v_lshl_add_u64 v[20:21], v[20:21], 0, s[40:41]
	v_lshl_add_u64 v[22:23], v[22:23], 0, s[40:41]
	v_lshl_add_u64 v[24:25], v[24:25], 0, s[40:41]
	v_lshl_add_u64 v[26:27], v[26:27], 0, s[40:41]
	v_lshl_add_u64 v[28:29], v[28:29], 0, s[40:41]
	v_lshl_add_u64 v[30:31], v[30:31], 0, s[40:41]
	global_load_dword v56, v[16:17], off nt
	global_load_dword v57, v[18:19], off nt
	global_load_dword v58, v[20:21], off nt
	global_load_dword v59, v[22:23], off nt
	global_load_dword v60, v[24:25], off nt
	global_load_dword v61, v[26:27], off nt
	global_load_dword v62, v[28:29], off nt
	global_load_dword v63, v[30:31], off nt
	v_lshl_add_u64 v[64:65], s[10:11], 0, v[124:125]
	v_lshl_add_u64 v[66:67], v[64:65], 0, s[42:43]
	v_lshl_add_u64 v[68:69], v[66:67], 0, s[42:43]
	v_lshl_add_u64 v[70:71], v[68:69], 0, s[42:43]
	s_add_i32 s31, s2, 0x300
	s_lshr_b32 s8, s31, 11
	s_and_b32 s9, s31, 0x7ff
; #define WAVE_LDS_SYNC() do { int _z = 0; (void)emu::wave_xchg(&_z, 4); } while (0)
; #define LAS __attribute__((address_space(3)))
; #define WAVE_LDS_SYNC() asm volatile("s_waitcnt lgkmcnt(0)" ::: "memory")
; #define NT_LOAD(p) __builtin_nontemporal_load(p)
; DEV void tr_item(const float* W, int ldw, int col0, int k0, bf16_t* WT, int K, int row0, LAS float* scr, int lane) {
; #pragma unroll 8
;     for (int i = 0; i < 32; ++i) { const int kk = 2 * i + (lane >> 5); scr[kk * 33 + (lane & 31)] = NT_LOAD(&W[(size_t)(k0 + kk) * ldw + col0 + (lane & 31)]); }
;     WAVE_LDS_SYNC();
	s_lshr_b32 s10, s9, 7
	s_and_b32 s9, s9, 0x7f
	s_lshl_b32 s24, s10, 19
	s_lshr_b32 s25, s9, 3
	s_lshl_b32 s25, s25, 9
	s_add_i32 s24, s24, s25
	s_and_b32 s25, s9, 3
	s_lshl_b32 s25, s25, 7
	s_add_i32 s24, s24, s25
	s_lshr_b32 s29, s8, 9
	s_lshl_b32 s28, s8, 23
	s_add_u32 s28, s28, s24
	s_addc_u32 s29, s29, 0
	s_bitcmp0_b32 s9, 2
	s_cselect_b32 s24, s4, s34
	s_cselect_b32 s25, s5, s35
	s_add_u32 s28, s28, s24
	s_addc_u32 s29, s29, s25
	s_lshl_b32 s24, s9, 16
	s_lshl_b32 s25, s10, 7
	s_add_i32 s24, s24, s25
	s_lshr_b32 s11, s8, 9
	s_lshl_b32 s10, s8, 23
	s_add_u32 s10, s10, s24
	s_addc_u32 s11, s11, 0
	s_add_u32 s10, s10, s6
	s_addc_u32 s11, s11, s7
	v_lshl_add_u64 v[16:17], s[28:29], 0, v[122:123]
	v_lshl_add_u64 v[18:19], v[16:17], 0, s[44:45]
	v_lshl_add_u64 v[20:21], v[18:19], 0, s[44:45]
	v_lshl_add_u64 v[22:23], v[20:21], 0, s[44:45]
	v_lshl_add_u64 v[24:25], v[22:23], 0, s[44:45]
	v_lshl_add_u64 v[26:27], v[24:25], 0, s[44:45]
	v_lshl_add_u64 v[28:29], v[26:27], 0, s[44:45]
	v_lshl_add_u64 v[30:31], v[28:29], 0, s[44:45]
	global_load_dword v162, v[16:17], off nt
	global_load_dword v163, v[18:19], off nt
	global_load_dword v164, v[20:21], off nt
	global_load_dword v165, v[22:23], off nt
	global_load_dword v166, v[24:25], off nt
	global_load_dword v167, v[26:27], off nt
	global_load_dword v168, v[28:29], off nt
	global_load_dword v169, v[30:31], off nt
	v_lshl_add_u64 v[16:17], v[16:17], 0, s[40:41]
	v_lshl_add_u64 v[18:19], v[18:19], 0, s[40:41]
	v_lshl_add_u64 v[20:21], v[20:21], 0, s[40:41]
	v_lshl_add_u64 v[22:23], v[22:23], 0, s[40:41]
	v_lshl_add_u64 v[24:25], v[24:25], 0, s[40:41]
	v_lshl_add_u64 v[26:27], v[26:27], 0, s[40:41]
	v_lshl_add_u64 v[28:29], v[28:29], 0, s[40:41]
	v_lshl_add_u64 v[30:31], v[30:31], 0, s[40:41]
	global_load_dword v170, v[16:17], off nt
	global_load_dword v171, v[18:19], off nt
	global_load_dword v172, v[20:21], off nt
	global_load_dword v173, v[22:23], off nt
	global_load_dword v174, v[24:25], off nt
	global_load_dword v175, v[26:27], off nt
	global_load_dword v176, v[28:29], off nt
	global_load_dword v177, v[30:31], off nt
	v_lshl_add_u64 v[16:17], v[16:17], 0, s[40:41]
	v_lshl_add_u64 v[18:19], v[18:19], 0, s[40:41]
	v_lshl_add_u64 v[20:21], v[20:21], 0, s[40:41]
	v_lshl_add_u64 v[22:23], v[22:23], 0, s[40:41]
	v_lshl_add_u64 v[24:25], v[24:25], 0, s[40:41]
	v_lshl_add_u64 v[26:27], v[26:27], 0, s[40:41]
	v_lshl_add_u64 v[28:29], v[28:29], 0, s[40:41]
	v_lshl_add_u64 v[30:31], v[30:31], 0, s[40:41]
	global_load_dword v178, v[16:17], off nt
	global_load_dword v179, v[18:19], off nt
	global_load_dword v180, v[20:21], off nt
	global_load_dword v181, v[22:23], off nt
	global_load_dword v182, v[24:25], off nt
	global_load_dword v183, v[26:27], off nt
	global_load_dword v184, v[28:29], off nt
	global_load_dword v185, v[30:31], off nt
	v_lshl_add_u64 v[16:17], v[16:17], 0, s[40:41]
	v_lshl_add_u64 v[18:19], v[18:19], 0, s[40:41]
	v_lshl_add_u64 v[20:21], v[20:21], 0, s[40:41]
	v_lshl_add_u64 v[22:23], v[22:23], 0, s[40:41]
	v_lshl_add_u64 v[24:25], v[24:25], 0, s[40:41]
	v_lshl_add_u64 v[26:27], v[26:27], 0, s[40:41]
	v_lshl_add_u64 v[28:29], v[28:29], 0, s[40:41]
	v_lshl_add_u64 v[30:31], v[30:31], 0, s[40:41]
	global_load_dword v186, v[16:17], off nt
	global_load_dword v187, v[18:19], off nt
	global_load_dword v188, v[20:21], off nt
	global_load_dword v189, v[22:23], off nt
	global_load_dword v190, v[24:25], off nt
	global_load_dword v191, v[26:27], off nt
	global_load_dword v192, v[28:29], off nt
	global_load_dword v193, v[30:31], off nt
	v_lshl_add_u64 v[126:127], s[10:11], 0, v[124:125]
	v_lshl_add_u64 v[128:129], v[126:127], 0, s[42:43]
	v_lshl_add_u64 v[130:131], v[128:129], 0, s[42:43]
	v_lshl_add_u64 v[132:133], v[130:131], 0, s[42:43]
	s_waitcnt vmcnt(62)
	ds_write2_b32 v7, v32, v33 offset1:66
	s_waitcnt vmcnt(60)
	ds_write2_b32 v7, v34, v35 offset0:132 offset1:198
	s_waitcnt vmcnt(58)
	ds_write2_b32 v8, v36, v37 offset0:8 offset1:74
	s_waitcnt vmcnt(56)
	ds_write2_b32 v8, v38, v39 offset0:140 offset1:206
	s_waitcnt vmcnt(54)
	ds_write2_b32 v9, v40, v41 offset1:66
	s_waitcnt vmcnt(52)
	ds_write2_b32 v9, v42, v43 offset0:132 offset1:198
	s_waitcnt vmcnt(50)
	ds_write2_b32 v10, v44, v45 offset0:8 offset1:74
	s_waitcnt vmcnt(48)
	ds_write2_b32 v10, v46, v47 offset0:140 offset1:206
	s_waitcnt vmcnt(46)
	ds_write2_b32 v11, v48, v49 offset1:66
	s_waitcnt vmcnt(44)
	ds_write2_b32 v11, v50, v51 offset0:132 offset1:198
	s_waitcnt vmcnt(42)
	ds_write2_b32 v12, v52, v53 offset0:8 offset1:74
	s_waitcnt vmcnt(40)
	ds_write2_b32 v12, v54, v55 offset0:140 offset1:206
	s_waitcnt vmcnt(38)
	ds_write2_b32 v13, v56, v57 offset1:66
	s_waitcnt vmcnt(36)
; #define WAVE_LDS_SYNC() do { int _z = 0; (void)emu::wave_xchg(&_z, 4); } while (0)
; #define LAS __attribute__((address_space(3)))
; #define WAVE_LDS_SYNC() asm volatile("s_waitcnt lgkmcnt(0)" ::: "memory")
; #define NT_STORE(v, p) __builtin_nontemporal_store((v), (p))
; DEV unsigned pk2(float lo, float hi) { return f2bf(lo) | (f2bf(hi) << 16); }
; DEV unsigned pk2(float lo, float hi) { const f32x2n_t v = {lo, hi}; return __builtin_bit_cast(unsigned, __builtin_convertvector(v, bf16x2n_t)); }
; DEV void tr_item(const float* W, int ldw, int col0, int k0, bf16_t* WT, int K, int row0, LAS float* scr, int lane) {
;     ...
;     WAVE_LDS_SYNC();
;     const int c = lane & 7;
; #pragma unroll
;     for (int j = 0; j < 4; ++j) { const int n = (lane >> 3) + 8 * j; const LAS float* s = scr + (8 * c) * 33 + n;
;         u32x4 o; o.x = pk2(s[0 * 33], s[1 * 33]); o.y = pk2(s[2 * 33], s[3 * 33]); o.z = pk2(s[4 * 33], s[5 * 33]); o.w = pk2(s[6 * 33], s[7 * 33]);
;         NT_STORE(o, (u32x4*)(WT + (size_t)(row0 + n) * K + k0 + 8 * c)); }
	ds_write2_b32 v13, v58, v59 offset0:132 offset1:198
	s_waitcnt vmcnt(34)
	ds_write2_b32 v14, v60, v61 offset0:8 offset1:74
	s_waitcnt vmcnt(32)
	ds_write2_b32 v14, v62, v63 offset0:140 offset1:206
	ds_read2_b32 v[72:73], v15 offset1:8
	ds_read2_b32 v[74:75], v15 offset0:33 offset1:41
	ds_read2_b32 v[76:77], v15 offset0:66 offset1:74
	ds_read2_b32 v[78:79], v15 offset0:99 offset1:107
	ds_read2_b32 v[80:81], v15 offset0:132 offset1:140
	ds_read2_b32 v[82:83], v15 offset0:165 offset1:173
	ds_read2_b32 v[84:85], v15 offset0:198 offset1:206
	ds_read2_b32 v[86:87], v15 offset0:231 offset1:239
	ds_read2_b32 v[88:89], v15 offset0:16 offset1:24
	ds_read2_b32 v[90:91], v15 offset0:49 offset1:57
	ds_read2_b32 v[92:93], v15 offset0:82 offset1:90
	ds_read2_b32 v[94:95], v15 offset0:115 offset1:123
	s_waitcnt lgkmcnt(4)
	v_cvt_pk_bf16_f32 v104, v72, v74
	v_cvt_pk_bf16_f32 v105, v76, v78
	v_cvt_pk_bf16_f32 v106, v80, v82
	v_cvt_pk_bf16_f32 v107, v84, v86
	v_cvt_pk_bf16_f32 v108, v73, v75
	v_cvt_pk_bf16_f32 v109, v77, v79
	v_cvt_pk_bf16_f32 v110, v81, v83
	v_cvt_pk_bf16_f32 v111, v85, v87
	ds_read2_b32 v[96:97], v15 offset0:148 offset1:156
	ds_read2_b32 v[98:99], v15 offset0:181 offset1:189
	ds_read2_b32 v[100:101], v15 offset0:214 offset1:222
	ds_read2_b32 v[102:103], v15 offset0:247 offset1:255
	global_store_dwordx4 v[64:65], v[104:107], off nt
	global_store_dwordx4 v[66:67], v[108:111], off nt
	s_waitcnt lgkmcnt(0)
	v_cvt_pk_bf16_f32 v112, v88, v90
	v_cvt_pk_bf16_f32 v113, v92, v94
	v_cvt_pk_bf16_f32 v114, v96, v98
	v_cvt_pk_bf16_f32 v115, v100, v102
	v_cvt_pk_bf16_f32 v116, v89, v91
	v_cvt_pk_bf16_f32 v117, v93, v95
	v_cvt_pk_bf16_f32 v118, v97, v99
	v_cvt_pk_bf16_f32 v119, v101, v103
	global_store_dwordx4 v[68:69], v[112:115], off nt
	global_store_dwordx4 v[70:71], v[116:119], off nt
	s_waitcnt vmcnt(34)
	ds_write2_b32 v7, v162, v163 offset1:66
	s_waitcnt vmcnt(32)
	ds_write2_b32 v7, v164, v165 offset0:132 offset1:198
	s_waitcnt vmcnt(30)
	ds_write2_b32 v8, v166, v167 offset0:8 offset1:74
	s_waitcnt vmcnt(28)
	ds_write2_b32 v8, v168, v169 offset0:140 offset1:206
	s_waitcnt vmcnt(26)
	ds_write2_b32 v9, v170, v171 offset1:66
	s_waitcnt vmcnt(24)
	ds_write2_b32 v9, v172, v173 offset0:132 offset1:198
	s_waitcnt vmcnt(22)
	ds_write2_b32 v10, v174, v175 offset0:8 offset1:74
	s_waitcnt vmcnt(20)
	ds_write2_b32 v10, v176, v177 offset0:140 offset1:206
	s_waitcnt vmcnt(18)
	ds_write2_b32 v11, v178, v179 offset1:66
	s_waitcnt vmcnt(16)
	ds_write2_b32 v11, v180, v181 offset0:132 offset1:198
	s_waitcnt vmcnt(14)
	ds_write2_b32 v12, v182, v183 offset0:8 offset1:74
	s_waitcnt vmcnt(12)
	ds_write2_b32 v12, v184, v185 offset0:140 offset1:206
	s_waitcnt vmcnt(10)
	ds_write2_b32 v13, v186, v187 offset1:66
	s_waitcnt vmcnt(8)
	ds_write2_b32 v13, v188, v189 offset0:132 offset1:198
	s_waitcnt vmcnt(6)
	ds_write2_b32 v14, v190, v191 offset0:8 offset1:74
	s_waitcnt vmcnt(4)
	ds_write2_b32 v14, v192, v193 offset0:140 offset1:206
	ds_read2_b32 v[72:73], v15 offset1:8
	ds_read2_b32 v[74:75], v15 offset0:33 offset1:41
	ds_read2_b32 v[76:77], v15 offset0:66 offset1:74
	ds_read2_b32 v[78:79], v15 offset0:99 offset1:107
	ds_read2_b32 v[80:81], v15 offset0:132 offset1:140
	ds_read2_b32 v[82:83], v15 offset0:165 offset1:173
	ds_read2_b32 v[84:85], v15 offset0:198 offset1:206
	ds_read2_b32 v[86:87], v15 offset0:231 offset1:239
	ds_read2_b32 v[88:89], v15 offset0:16 offset1:24
	ds_read2_b32 v[90:91], v15 offset0:49 offset1:57
	ds_read2_b32 v[92:93], v15 offset0:82 offset1:90
	ds_read2_b32 v[94:95], v15 offset0:115 offset1:123
	s_waitcnt lgkmcnt(4)
	v_cvt_pk_bf16_f32 v104, v72, v74
	v_cvt_pk_bf16_f32 v105, v76, v78
	v_cvt_pk_bf16_f32 v106, v80, v82
	v_cvt_pk_bf16_f32 v107, v84, v86
	v_cvt_pk_bf16_f32 v108, v73, v75
	v_cvt_pk_bf16_f32 v109, v77, v79
	v_cvt_pk_bf16_f32 v110, v81, v83
	v_cvt_pk_bf16_f32 v111, v85, v87
	ds_read2_b32 v[96:97], v15 offset0:148 offset1:156
	ds_read2_b32 v[98:99], v15 offset0:181 offset1:189
	ds_read2_b32 v[100:101], v15 offset0:214 offset1:222
	ds_read2_b32 v[102:103], v15 offset0:247 offset1:255
	global_store_dwordx4 v[126:127], v[104:107], off nt
	global_store_dwordx4 v[128:129], v[108:111], off nt
	s_waitcnt lgkmcnt(0)
	v_cvt_pk_bf16_f32 v112, v88, v90
	v_cvt_pk_bf16_f32 v113, v92, v94
	v_cvt_pk_bf16_f32 v114, v96, v98
	v_cvt_pk_bf16_f32 v115, v100, v102
	v_cvt_pk_bf16_f32 v116, v89, v91
	v_cvt_pk_bf16_f32 v117, v93, v95
	v_cvt_pk_bf16_f32 v118, v97, v99
	v_cvt_pk_bf16_f32 v119, v101, v103
	global_store_dwordx4 v[130:131], v[112:115], off nt
	global_store_dwordx4 v[132:133], v[116:119], off nt
	s_add_i32 s2, s2, 0x600
	s_cmp_lt_u32 s2, s101
	s_cbranch_scc1 .Lsg_loop

; #define LAS __attribute__((address_space(3)))
; #define NT_LOAD(p) __builtin_nontemporal_load(p)
; DEV void tr_item(const float* W, int ldw, int col0, int k0, bf16_t* WT, int K, int row0, LAS float* scr, int lane) {
; #pragma unroll 8
;     for (int i = 0; i < 32; ++i) { const int kk = 2 * i + (lane >> 5); scr[kk * 33 + (lane & 31)] = NT_LOAD(&W[(size_t)(k0 + kk) * ldw + col0 + (lane & 31)]); }
; DEV void phase_prologue_a(const Frame& F0) {
;     ...
;         constexpr int D_ITEMS = (FF / 64) * 32;
;         for (int it = F.gw; it < NE * D_ITEMS; it += F.NGW) { const int e = it / D_ITEMS, r = it % D_ITEMS, kb = r / 32, nb = r % 32;
;             tr_item(GIN(I_WDOWN) + ((size_t)l * NE + e) * FF * 1024, 1024, 32 * nb, 64 * kb, (bf16_t*)(F.ws + WS_WD) + ((size_t)l * NE + e) * 1024 * FF, FF, 32 * nb, scr, F.lane); }
.Lsd_loop:
	s_lshr_b32 s8, s2, 10
	s_and_b32 s9, s2, 0x3ff
	s_lshr_b32 s10, s9, 5
	s_and_b32 s9, s9, 31
	s_lshl_b32 s24, s10, 18
	s_lshl_b32 s25, s9, 7
	s_add_i32 s24, s24, s25
	s_lshr_b32 s29, s8, 9
	s_lshl_b32 s28, s8, 23
	s_add_u32 s28, s28, s24
	s_addc_u32 s29, s29, 0
	s_add_u32 s28, s28, s4
	s_addc_u32 s29, s29, s5
	s_lshl_b32 s24, s9, 17
	s_lshl_b32 s25, s10, 7
	s_add_i32 s24, s24, s25
	s_lshr_b32 s11, s8, 10
	s_lshl_b32 s10, s8, 22
	s_add_u32 s10, s10, s24
	s_addc_u32 s11, s11, 0
	s_add_u32 s10, s10, s6
	s_addc_u32 s11, s11, s7
	v_lshl_add_u64 v[16:17], s[28:29], 0, v[122:123]
	v_lshl_add_u64 v[18:19], v[16:17], 0, s[44:45]
	v_lshl_add_u64 v[20:21], v[18:19], 0, s[44:45]
	v_lshl_add_u64 v[22:23], v[20:21], 0, s[44:45]
	v_lshl_add_u64 v[24:25], v[22:23], 0, s[44:45]
	v_lshl_add_u64 v[26:27], v[24:25], 0, s[44:45]
	v_lshl_add_u64 v[28:29], v[26:27], 0, s[44:45]
	v_lshl_add_u64 v[30:31], v[28:29], 0, s[44:45]
	global_load_dword v32, v[16:17], off nt
	global_load_dword v33, v[18:19], off nt
	global_load_dword v34, v[20:21], off nt
	global_load_dword v35, v[22:23], off nt
	global_load_dword v36, v[24:25], off nt
	global_load_dword v37, v[26:27], off nt
	global_load_dword v38, v[28:29], off nt
	global_load_dword v39, v[30:31], off nt
	v_lshl_add_u64 v[16:17], v[16:17], 0, s[40:41]
	v_lshl_add_u64 v[18:19], v[18:19], 0, s[40:41]
	v_lshl_add_u64 v[20:21], v[20:21], 0, s[40:41]
	v_lshl_add_u64 v[22:23], v[22:23], 0, s[40:41]
	v_lshl_add_u64 v[24:25], v[24:25], 0, s[40:41]
	v_lshl_add_u64 v[26:27], v[26:27], 0, s[40:41]
	v_lshl_add_u64 v[28:29], v[28:29], 0, s[40:41]
	v_lshl_add_u64 v[30:31], v[30:31], 0, s[40:41]
	global_load_dword v40, v[16:17], off nt
	global_load_dword v41, v[18:19], off nt
	global_load_dword v42, v[20:21], off nt
	global_load_dword v43, v[22:23], off nt
	global_load_dword v44, v[24:25], off nt
	global_load_dword v45, v[26:27], off nt
	global_load_dword v46, v[28:29], off nt
	global_load_dword v47, v[30:31], off nt
	v_lshl_add_u64 v[16:17], v[16:17], 0, s[40:41]
	v_lshl_add_u64 v[18:19], v[18:19], 0, s[40:41]
	v_lshl_add_u64 v[20:21], v[20:21], 0, s[40:41]
	v_lshl_add_u64 v[22:23], v[22:23], 0, s[40:41]
	v_lshl_add_u64 v[24:25], v[24:25], 0, s[40:41]
	v_lshl_add_u64 v[26:27], v[26:27], 0, s[40:41]
	v_lshl_add_u64 v[28:29], v[28:29], 0, s[40:41]
	v_lshl_add_u64 v[30:31], v[30:31], 0, s[40:41]
	global_load_dword v48, v[16:17], off nt
	global_load_dword v49, v[18:19], off nt
	global_load_dword v50, v[20:21], off nt
	global_load_dword v51, v[22:23], off nt
	global_load_dword v52, v[24:25], off nt
	global_load_dword v53, v[26:27], off nt
	global_load_dword v54, v[28:29], off nt
	global_load_dword v55, v[30:31], off nt
	v_lshl_add_u64 v[16:17], v[16:17], 0, s[40:41]
	v_lshl_add_u64 v[18:19], v[18:19], 0, s[40:41]
	v_lshl_add_u64 v[20:21], v[20:21], 0, s[40:41]
	v_lshl_add_u64 v[22:23], v[22:23], 0, s[40:41]
	v_lshl_add_u64 v[24:25], v[24:25], 0, s[40:41]
	v_lshl_add_u64 v[26:27], v[26:27], 0, s[40:41]
	v_lshl_add_u64 v[28:29], v[28:29], 0, s[40:41]
	v_lshl_add_u64 v[30:31], v[30:31], 0, s[40:41]
	global_load_dword v56, v[16:17], off nt
	global_load_dword v57, v[18:19], off nt
	global_load_dword v58, v[20:21], off nt
	global_load_dword v59, v[22:23], off nt
	global_load_dword v60, v[24:25], off nt
	global_load_dword v61, v[26:27], off nt
	global_load_dword v62, v[28:29], off nt
	global_load_dword v63, v[30:31], off nt
	v_lshl_add_u64 v[64:65], s[10:11], 0, v[124:125]
	v_lshl_add_u64 v[66:67], v[64:65], 0, s[42:43]
	v_lshl_add_u64 v[68:69], v[66:67], 0, s[42:43]
	v_lshl_add_u64 v[70:71], v[68:69], 0, s[42:43]
	s_add_i32 s31, s2, 0x200
	s_lshr_b32 s8, s31, 10
	s_and_b32 s9, s31, 0x3ff
	s_lshr_b32 s10, s9, 5
	s_and_b32 s9, s9, 31
	s_lshl_b32 s24, s10, 18
	s_lshl_b32 s25, s9, 7
	s_add_i32 s24, s24, s25
	s_lshr_b32 s29, s8, 9
	s_lshl_b32 s28, s8, 23
	s_add_u32 s28, s28, s24
	s_addc_u32 s29, s29, 0
	s_add_u32 s28, s28, s4
	s_addc_u32 s29, s29, s5
	s_lshl_b32 s24, s9, 17
	s_lshl_b32 s25, s10, 7
	s_add_i32 s24, s24, s25
	s_lshr_b32 s11, s8, 10
	s_lshl_b32 s10, s8, 22
	s_add_u32 s10, s10, s24
	s_addc_u32 s11, s11, 0
	s_add_u32 s10, s10, s6
	s_addc_u32 s11, s11, s7
	v_lshl_add_u64 v[16:17], s[28:29], 0, v[122:123]
	v_lshl_add_u64 v[18:19], v[16:17], 0, s[44:45]
	v_lshl_add_u64 v[20:21], v[18:19], 0, s[44:45]
	v_lshl_add_u64 v[22:23], v[20:21], 0, s[44:45]
	v_lshl_add_u64 v[24:25], v[22:23], 0, s[44:45]
	v_lshl_add_u64 v[26:27], v[24:25], 0, s[44:45]
	v_lshl_add_u64 v[28:29], v[26:27], 0, s[44:45]
	v_lshl_add_u64 v[30:31], v[28:29], 0, s[44:45]
	global_load_dword v126, v[16:17], off nt
	global_load_dword v127, v[18:19], off nt
	global_load_dword v128, v[20:21], off nt
	global_load_dword v129, v[22:23], off nt
	global_load_dword v130, v[24:25], off nt
	global_load_dword v131, v[26:27], off nt
	global_load_dword v132, v[28:29], off nt
	global_load_dword v133, v[30:31], off nt
	v_lshl_add_u64 v[16:17], v[16:17], 0, s[40:41]
	v_lshl_add_u64 v[18:19], v[18:19], 0, s[40:41]
	v_lshl_add_u64 v[20:21], v[20:21], 0, s[40:41]
	v_lshl_add_u64 v[22:23], v[22:23], 0, s[40:41]
	v_lshl_add_u64 v[24:25], v[24:25], 0, s[40:41]
	v_lshl_add_u64 v[26:27], v[26:27], 0, s[40:41]
	v_lshl_add_u64 v[28:29], v[28:29], 0, s[40:41]
	v_lshl_add_u64 v[30:31], v[30:31], 0, s[40:41]
	global_load_dword v134, v[16:17], off nt
	global_load_dword v135, v[18:19], off nt
	global_load_dword v136, v[20:21], off nt
	global_load_dword v137, v[22:23], off nt
	global_load_dword v138, v[24:25], off nt
	global_load_dword v139, v[26:27], off nt
	global_load_dword v140, v[28:29], off nt
	global_load_dword v141, v[30:31], off nt
	v_lshl_add_u64 v[16:17], v[16:17], 0, s[40:41]
; #define WAVE_LDS_SYNC() do { int _z = 0; (void)emu::wave_xchg(&_z, 4); } while (0)
; #define LAS __attribute__((address_space(3)))
; #define WAVE_LDS_SYNC() asm volatile("s_waitcnt lgkmcnt(0)" ::: "memory")
; #define NT_LOAD(p) __builtin_nontemporal_load(p)
; #define NT_STORE(v, p) __builtin_nontemporal_store((v), (p))
; DEV unsigned pk2(float lo, float hi) { return f2bf(lo) | (f2bf(hi) << 16); }
; DEV unsigned pk2(float lo, float hi) { const f32x2n_t v = {lo, hi}; return __builtin_bit_cast(unsigned, __builtin_convertvector(v, bf16x2n_t)); }
; DEV void tr_item(const float* W, int ldw, int col0, int k0, bf16_t* WT, int K, int row0, LAS float* scr, int lane) {
; #pragma unroll 8
;     for (int i = 0; i < 32; ++i) { const int kk = 2 * i + (lane >> 5); scr[kk * 33 + (lane & 31)] = NT_LOAD(&W[(size_t)(k0 + kk) * ldw + col0 + (lane & 31)]); }
;     WAVE_LDS_SYNC();
;     const int c = lane & 7;
; #pragma unroll
;     for (int j = 0; j < 4; ++j) { const int n = (lane >> 3) + 8 * j; const LAS float* s = scr + (8 * c) * 33 + n;
;         u32x4 o; o.x = pk2(s[0 * 33], s[1 * 33]); o.y = pk2(s[2 * 33], s[3 * 33]); o.z = pk2(s[4 * 33], s[5 * 33]); o.w = pk2(s[6 * 33], s[7 * 33]);
;         NT_STORE(o, (u32x4*)(WT + (size_t)(row0 + n) * K + k0 + 8 * c)); }
	v_lshl_add_u64 v[18:19], v[18:19], 0, s[40:41]
	v_lshl_add_u64 v[20:21], v[20:21], 0, s[40:41]
	v_lshl_add_u64 v[22:23], v[22:23], 0, s[40:41]
	v_lshl_add_u64 v[24:25], v[24:25], 0, s[40:41]
	v_lshl_add_u64 v[26:27], v[26:27], 0, s[40:41]
	v_lshl_add_u64 v[28:29], v[28:29], 0, s[40:41]
	v_lshl_add_u64 v[30:31], v[30:31], 0, s[40:41]
	global_load_dword v142, v[16:17], off nt
	global_load_dword v143, v[18:19], off nt
	global_load_dword v144, v[20:21], off nt
	global_load_dword v145, v[22:23], off nt
	global_load_dword v150, v[24:25], off nt
	global_load_dword v151, v[26:27], off nt
	global_load_dword v152, v[28:29], off nt
	global_load_dword v153, v[30:31], off nt
	v_lshl_add_u64 v[16:17], v[16:17], 0, s[40:41]
	v_lshl_add_u64 v[18:19], v[18:19], 0, s[40:41]
	v_lshl_add_u64 v[20:21], v[20:21], 0, s[40:41]
	v_lshl_add_u64 v[22:23], v[22:23], 0, s[40:41]
	v_lshl_add_u64 v[24:25], v[24:25], 0, s[40:41]
	v_lshl_add_u64 v[26:27], v[26:27], 0, s[40:41]
	v_lshl_add_u64 v[28:29], v[28:29], 0, s[40:41]
	v_lshl_add_u64 v[30:31], v[30:31], 0, s[40:41]
	global_load_dword v154, v[16:17], off nt
	global_load_dword v155, v[18:19], off nt
	global_load_dword v156, v[20:21], off nt
	global_load_dword v157, v[22:23], off nt
	global_load_dword v158, v[24:25], off nt
	global_load_dword v159, v[26:27], off nt
	global_load_dword v160, v[28:29], off nt
	global_load_dword v161, v[30:31], off nt
	v_lshl_add_u64 v[162:163], s[10:11], 0, v[124:125]
	v_lshl_add_u64 v[164:165], v[162:163], 0, s[42:43]
	v_lshl_add_u64 v[166:167], v[164:165], 0, s[42:43]
	v_lshl_add_u64 v[168:169], v[166:167], 0, s[42:43]
	s_waitcnt vmcnt(62)
	ds_write2_b32 v7, v32, v33 offset1:66
	s_waitcnt vmcnt(60)
	ds_write2_b32 v7, v34, v35 offset0:132 offset1:198
	s_waitcnt vmcnt(58)
	ds_write2_b32 v8, v36, v37 offset0:8 offset1:74
	s_waitcnt vmcnt(56)
	ds_write2_b32 v8, v38, v39 offset0:140 offset1:206
	s_waitcnt vmcnt(54)
	ds_write2_b32 v9, v40, v41 offset1:66
	s_waitcnt vmcnt(52)
	ds_write2_b32 v9, v42, v43 offset0:132 offset1:198
	s_waitcnt vmcnt(50)
	ds_write2_b32 v10, v44, v45 offset0:8 offset1:74
	s_waitcnt vmcnt(48)
	ds_write2_b32 v10, v46, v47 offset0:140 offset1:206
	s_waitcnt vmcnt(46)
	ds_write2_b32 v11, v48, v49 offset1:66
	s_waitcnt vmcnt(44)
	ds_write2_b32 v11, v50, v51 offset0:132 offset1:198
	s_waitcnt vmcnt(42)
	ds_write2_b32 v12, v52, v53 offset0:8 offset1:74
	s_waitcnt vmcnt(40)
	ds_write2_b32 v12, v54, v55 offset0:140 offset1:206
	s_waitcnt vmcnt(38)
	ds_write2_b32 v13, v56, v57 offset1:66
	s_waitcnt vmcnt(36)
	ds_write2_b32 v13, v58, v59 offset0:132 offset1:198
	s_waitcnt vmcnt(34)
	ds_write2_b32 v14, v60, v61 offset0:8 offset1:74
	s_waitcnt vmcnt(32)
	ds_write2_b32 v14, v62, v63 offset0:140 offset1:206
	ds_read2_b32 v[72:73], v15 offset1:8
	ds_read2_b32 v[74:75], v15 offset0:33 offset1:41
	ds_read2_b32 v[76:77], v15 offset0:66 offset1:74
	ds_read2_b32 v[78:79], v15 offset0:99 offset1:107
	ds_read2_b32 v[80:81], v15 offset0:132 offset1:140
	ds_read2_b32 v[82:83], v15 offset0:165 offset1:173
	ds_read2_b32 v[84:85], v15 offset0:198 offset1:206
	ds_read2_b32 v[86:87], v15 offset0:231 offset1:239
	ds_read2_b32 v[88:89], v15 offset0:16 offset1:24
	ds_read2_b32 v[90:91], v15 offset0:49 offset1:57
	ds_read2_b32 v[92:93], v15 offset0:82 offset1:90
	ds_read2_b32 v[94:95], v15 offset0:115 offset1:123
	s_waitcnt lgkmcnt(4)
	v_cvt_pk_bf16_f32 v104, v72, v74
	v_cvt_pk_bf16_f32 v105, v76, v78
	v_cvt_pk_bf16_f32 v106, v80, v82
	v_cvt_pk_bf16_f32 v107, v84, v86
	v_cvt_pk_bf16_f32 v108, v73, v75
	v_cvt_pk_bf16_f32 v109, v77, v79
	v_cvt_pk_bf16_f32 v110, v81, v83
	v_cvt_pk_bf16_f32 v111, v85, v87
	ds_read2_b32 v[96:97], v15 offset0:148 offset1:156
	ds_read2_b32 v[98:99], v15 offset0:181 offset1:189
	ds_read2_b32 v[100:101], v15 offset0:214 offset1:222
	ds_read2_b32 v[102:103], v15 offset0:247 offset1:255
	global_store_dwordx4 v[64:65], v[104:107], off nt
	global_store_dwordx4 v[66:67], v[108:111], off nt
	s_waitcnt lgkmcnt(0)
; #define LAS __attribute__((address_space(3)))
; #define NT_STORE(v, p) __builtin_nontemporal_store((v), (p))
; DEV unsigned pk2(float lo, float hi) { return f2bf(lo) | (f2bf(hi) << 16); }
; DEV unsigned pk2(float lo, float hi) { const f32x2n_t v = {lo, hi}; return __builtin_bit_cast(unsigned, __builtin_convertvector(v, bf16x2n_t)); }
; DEV void tr_item(const float* W, int ldw, int col0, int k0, bf16_t* WT, int K, int row0, LAS float* scr, int lane) {
;     ...
; #pragma unroll
;     for (int j = 0; j < 4; ++j) { const int n = (lane >> 3) + 8 * j; const LAS float* s = scr + (8 * c) * 33 + n;
;         u32x4 o; o.x = pk2(s[0 * 33], s[1 * 33]); o.y = pk2(s[2 * 33], s[3 * 33]); o.z = pk2(s[4 * 33], s[5 * 33]); o.w = pk2(s[6 * 33], s[7 * 33]);
;         NT_STORE(o, (u32x4*)(WT + (size_t)(row0 + n) * K + k0 + 8 * c)); }
; DEV void phase_prologue_a(const Frame& F0) {
;     ...
;         constexpr int GU_NB = 2 * FF / 32, GU_ITEMS = 16 * GU_NB;
;         for (int it = F.gw; it < NE * GU_ITEMS; it += F.NGW) { const int e = it / GU_ITEMS, r = it % GU_ITEMS, kb = r / GU_NB, nb = r % GU_NB; const int d0 = 32 * nb, j = d0 >> 8, w = d0 & 255;
;             const float* src = (w < 128 ? GIN(I_WGATE) : GIN(I_WUP)) + ((size_t)l * NE + e) * 1024 * FF;
;             tr_item(src, FF, 128 * j + (w & 127), 64 * kb, (bf16_t*)(F.ws + WS_WGU) + ((size_t)l * NE + e) * 2 * FF * 1024, 1024, d0, scr, F.lane); }
	v_cvt_pk_bf16_f32 v112, v88, v90
	v_cvt_pk_bf16_f32 v113, v92, v94
	v_cvt_pk_bf16_f32 v114, v96, v98
	v_cvt_pk_bf16_f32 v115, v100, v102
	v_cvt_pk_bf16_f32 v116, v89, v91
	v_cvt_pk_bf16_f32 v117, v93, v95
	v_cvt_pk_bf16_f32 v118, v97, v99
	v_cvt_pk_bf16_f32 v119, v101, v103
	global_store_dwordx4 v[68:69], v[112:115], off nt
	global_store_dwordx4 v[70:71], v[116:119], off nt
	s_waitcnt vmcnt(34)
	ds_write2_b32 v7, v126, v127 offset1:66
	s_waitcnt vmcnt(32)
	ds_write2_b32 v7, v128, v129 offset0:132 offset1:198
	s_waitcnt vmcnt(30)
	ds_write2_b32 v8, v130, v131 offset0:8 offset1:74
	s_waitcnt vmcnt(28)
	ds_write2_b32 v8, v132, v133 offset0:140 offset1:206
	s_waitcnt vmcnt(26)
	ds_write2_b32 v9, v134, v135 offset1:66
	s_waitcnt vmcnt(24)
	ds_write2_b32 v9, v136, v137 offset0:132 offset1:198
	s_waitcnt vmcnt(22)
	ds_write2_b32 v10, v138, v139 offset0:8 offset1:74
	s_waitcnt vmcnt(20)
	ds_write2_b32 v10, v140, v141 offset0:140 offset1:206
	s_waitcnt vmcnt(18)
	ds_write2_b32 v11, v142, v143 offset1:66
	s_waitcnt vmcnt(16)
	ds_write2_b32 v11, v144, v145 offset0:132 offset1:198
	s_waitcnt vmcnt(14)
	ds_write2_b32 v12, v150, v151 offset0:8 offset1:74
	s_waitcnt vmcnt(12)
	ds_write2_b32 v12, v152, v153 offset0:140 offset1:206
	s_waitcnt vmcnt(10)
	ds_write2_b32 v13, v154, v155 offset1:66
	s_waitcnt vmcnt(8)
	ds_write2_b32 v13, v156, v157 offset0:132 offset1:198
	s_waitcnt vmcnt(6)
	ds_write2_b32 v14, v158, v159 offset0:8 offset1:74
	s_waitcnt vmcnt(4)
	ds_write2_b32 v14, v160, v161 offset0:140 offset1:206
	ds_read2_b32 v[72:73], v15 offset1:8
	ds_read2_b32 v[74:75], v15 offset0:33 offset1:41
	ds_read2_b32 v[76:77], v15 offset0:66 offset1:74
	ds_read2_b32 v[78:79], v15 offset0:99 offset1:107
	ds_read2_b32 v[80:81], v15 offset0:132 offset1:140
	ds_read2_b32 v[82:83], v15 offset0:165 offset1:173
	ds_read2_b32 v[84:85], v15 offset0:198 offset1:206
	ds_read2_b32 v[86:87], v15 offset0:231 offset1:239
	ds_read2_b32 v[88:89], v15 offset0:16 offset1:24
	ds_read2_b32 v[90:91], v15 offset0:49 offset1:57
	ds_read2_b32 v[92:93], v15 offset0:82 offset1:90
	ds_read2_b32 v[94:95], v15 offset0:115 offset1:123
	s_waitcnt lgkmcnt(4)
	v_cvt_pk_bf16_f32 v104, v72, v74
	v_cvt_pk_bf16_f32 v105, v76, v78
	v_cvt_pk_bf16_f32 v106, v80, v82
	v_cvt_pk_bf16_f32 v107, v84, v86
	v_cvt_pk_bf16_f32 v108, v73, v75
	v_cvt_pk_bf16_f32 v109, v77, v79
	v_cvt_pk_bf16_f32 v110, v81, v83
	v_cvt_pk_bf16_f32 v111, v85, v87
	ds_read2_b32 v[96:97], v15 offset0:148 offset1:156
	ds_read2_b32 v[98:99], v15 offset0:181 offset1:189
	ds_read2_b32 v[100:101], v15 offset0:214 offset1:222
	ds_read2_b32 v[102:103], v15 offset0:247 offset1:255
	global_store_dwordx4 v[162:163], v[104:107], off nt
	global_store_dwordx4 v[164:165], v[108:111], off nt
	s_waitcnt lgkmcnt(0)
	v_cvt_pk_bf16_f32 v112, v88, v90
	v_cvt_pk_bf16_f32 v113, v92, v94
	v_cvt_pk_bf16_f32 v114, v96, v98
	v_cvt_pk_bf16_f32 v115, v100, v102
	v_cvt_pk_bf16_f32 v116, v89, v91
	v_cvt_pk_bf16_f32 v117, v93, v95
	v_cvt_pk_bf16_f32 v118, v97, v99
	v_cvt_pk_bf16_f32 v119, v101, v103
	global_store_dwordx4 v[166:167], v[112:115], off nt
	global_store_dwordx4 v[168:169], v[116:119], off nt
	s_addk_i32 s2, 0x400
	s_cmp_lt_u32 s2, 0x4000
	s_cbranch_scc1 .Lsd_loop
	s_mov_b32 s36, 2
	s_mov_b32 s37, 0x7600
	s_mov_b32 s101, 0x8000
	s_cmp_eq_u32 s0, 1
	s_cbranch_scc1 .Lsx_go
	s_mov_b32 s36, 3
	s_mov_b32 s37, 0x4d00
	s_mov_b32 s101, 0x5900
	s_cmp_eq_u32 s0, 2
	s_cbranch_scc1 .Lsx_go
	s_mov_b32 s37, 0x5900
	s_mov_b32 s101, 0x6500
